# seams: agent-scope acquire (buffer_inv sc1) issued at arrival right after the arrival atomic instead of after the release is observed (L1 untouched between arrival and release: only sc1 polls), remove
# speedup vs baseline: 1.0173x; 1.0037x over previous
; __device__ __forceinline__ unsigned xb_ld(unsigned* p)              { return __hip_atomic_load(p, __ATOMIC_RELAXED, __HIP_MEMORY_SCOPE_AGENT); }
; __device__ __forceinline__ unsigned xb_add(unsigned* p, unsigned v) { return __hip_atomic_fetch_add(p, v, __ATOMIC_RELAXED, __HIP_MEMORY_SCOPE_AGENT); }
; #define XB_SPIN(cond, bar) do { unsigned _sp = 0; while (cond) { __builtin_amdgcn_s_sleep(1); \
;     if ((++_sp & 255u) == 0u) { if (xb_ld(&(bar)[XB_TMO])) break; if (_sp > XB_SPIN_CAP) { atomicAdd(&(bar)[XB_TMO], 1u); break; } } } } while (0)
; __device__ __forceinline__ void xcd_barrier(const XcdBarrier& b) {
;     ...
;         unsigned nloc = b.st[0], nx = b.st[1];
;         if (nloc == 0u) { xcd_barrier_complete(bar, b.x, nloc, nx); b.st[0] = nloc; b.st[1] = nx; }
;         const unsigned old = xb_add(&bar[XB_XSUB(b.x)], 1u);
;         const unsigned gen = old / nloc;
;         if (old + 1u == (gen + 1u) * nloc) {
;             __builtin_amdgcn_fence(__ATOMIC_RELEASE, "agent");
;             asm volatile("s_waitcnt vmcnt(0)" ::: "memory");
;             const unsigned og = xb_add(&bar[XB_TOP], 1u);
;             const unsigned tg = og / nx;
;             if (og + 1u == (tg + 1u) * nx) xb_add(&bar[XB_TOPGEN], 1u);
;             else XB_SPIN(xb_ld(&bar[XB_TOPGEN]) == tg, bar);
;             __builtin_amdgcn_fence(__ATOMIC_ACQUIRE, "agent");
;             xb_add(&bar[XB_XGEN(b.x)], 1u);
;             asm volatile("s_waitcnt vmcnt(0)" ::: "memory");
;         } else {
;             XB_SPIN(xb_ld(&bar[XB_XGEN(b.x)]) == gen, bar);
.LBB0_151:
	s_lshl_b32 s6, s65, 8
	v_readlane_b32 s8, v247, 16
	v_readlane_b32 s9, v247, 17
	s_add_u32 s6, s8, s6
	s_addc_u32 s7, s9, 0
	v_mov_b32_e32 v1, 0x1000
	v_mov_b32_e32 v3, 1
	global_atomic_add v3, v1, v3, s[6:7] offset:1024 sc0
	buffer_inv sc1
	v_cvt_f32_u32_e32 v1, v2
	v_sub_u32_e32 v4, 0, v2
	v_rcp_iflag_f32_e32 v1, v1
	s_nop 0
	v_mul_f32_e32 v1, 0x4f7ffffe, v1
	v_cvt_u32_f32_e32 v1, v1
	v_mul_lo_u32 v4, v4, v1
	v_mul_hi_u32 v4, v1, v4
	v_add_u32_e32 v1, v1, v4
	s_waitcnt vmcnt(0)
	v_mul_hi_u32 v1, v3, v1
	v_mul_lo_u32 v4, v1, v2
	v_sub_u32_e32 v4, v3, v4
	v_add_u32_e32 v5, 1, v1
	v_cmp_ge_u32_e32 vcc, v4, v2
	v_add_u32_e32 v3, 1, v3
	s_nop 0
	v_cndmask_b32_e32 v1, v1, v5, vcc
	v_sub_u32_e32 v5, v4, v2
	v_cndmask_b32_e32 v4, v4, v5, vcc
	v_add_u32_e32 v5, 1, v1
	v_cmp_ge_u32_e32 vcc, v4, v2
	s_nop 1
	v_cndmask_b32_e32 v1, v1, v5, vcc
	v_mul_lo_u32 v4, v2, v1
	v_add_u32_e32 v2, v4, v2
	v_cmp_ne_u32_e32 vcc, v3, v2
	s_and_saveexec_b64 s[8:9], vcc
	s_xor_b64 s[8:9], exec, s[8:9]
	s_cbranch_execz .LBB0_165
	s_waitcnt lgkmcnt(0)
	v_mov_b32_e32 v0, 0x2000
	global_load_dword v0, v0, s[6:7] offset:1024 sc1
	s_add_u32 s14, s6, 0x2400
	s_addc_u32 s15, s7, 0
	s_waitcnt vmcnt(0)
	v_cmp_eq_u32_e32 vcc, v0, v1
	s_and_saveexec_b64 s[10:11], vcc
	s_cbranch_execz .LBB0_164
	s_add_u32 s12, s84, 0xc0200
	s_addc_u32 s13, s85, 0
	s_mov_b32 s26, 1
	s_mov_b64 s[16:17], 0
	v_mov_b32_e32 v0, 0
	s_branch .LBB0_155

; __device__ __forceinline__ unsigned xb_ld(unsigned* p)              { return __hip_atomic_load(p, __ATOMIC_RELAXED, __HIP_MEMORY_SCOPE_AGENT); }
; #define XB_SPIN(cond, bar) do { unsigned _sp = 0; while (cond) { __builtin_amdgcn_s_sleep(1); \
;     if ((++_sp & 255u) == 0u) { if (xb_ld(&(bar)[XB_TMO])) break; if (_sp > XB_SPIN_CAP) { atomicAdd(&(bar)[XB_TMO], 1u); break; } } } } while (0)
; __device__ __forceinline__ void xcd_barrier(const XcdBarrier& b) {
;     ...
;             XB_SPIN(xb_ld(&bar[XB_XGEN(b.x)]) == gen, bar);
;             __builtin_amdgcn_fence(__ATOMIC_ACQUIRE, "agent");
;             asm volatile("s_waitcnt vmcnt(0)" ::: "memory");
.LBB0_164:
	s_or_b64 exec, exec, s[10:11]
	s_waitcnt vmcnt(0)
	s_waitcnt vmcnt(0)

; __device__ __forceinline__ unsigned xb_ld(unsigned* p)              { return __hip_atomic_load(p, __ATOMIC_RELAXED, __HIP_MEMORY_SCOPE_AGENT); }
; __device__ __forceinline__ unsigned xb_add(unsigned* p, unsigned v) { return __hip_atomic_fetch_add(p, v, __ATOMIC_RELAXED, __HIP_MEMORY_SCOPE_AGENT); }
; #define XB_SPIN(cond, bar) do { unsigned _sp = 0; while (cond) { __builtin_amdgcn_s_sleep(1); \
;     if ((++_sp & 255u) == 0u) { if (xb_ld(&(bar)[XB_TMO])) break; if (_sp > XB_SPIN_CAP) { atomicAdd(&(bar)[XB_TMO], 1u); break; } } } } while (0)
; __device__ __forceinline__ void xcd_barrier(const XcdBarrier& b) {
;     ...
;             else XB_SPIN(xb_ld(&bar[XB_TOPGEN]) == tg, bar);
;             __builtin_amdgcn_fence(__ATOMIC_ACQUIRE, "agent");
;             xb_add(&bar[XB_XGEN(b.x)], 1u);
.LBB0_182:
	s_or_b64 exec, exec, s[8:9]
	v_mov_b32_e32 v0, 0x2000
	v_mov_b32_e32 v1, 1
	s_waitcnt vmcnt(0)
	global_atomic_add v0, v1, s[6:7] offset:1024
	s_waitcnt vmcnt(0)

; __device__ __forceinline__ unsigned xb_ld(unsigned* p)              { return __hip_atomic_load(p, __ATOMIC_RELAXED, __HIP_MEMORY_SCOPE_AGENT); }
; __device__ __forceinline__ unsigned xb_add(unsigned* p, unsigned v) { return __hip_atomic_fetch_add(p, v, __ATOMIC_RELAXED, __HIP_MEMORY_SCOPE_AGENT); }
; #define XB_SPIN(cond, bar) do { unsigned _sp = 0; while (cond) { __builtin_amdgcn_s_sleep(1); \
;     if ((++_sp & 255u) == 0u) { if (xb_ld(&(bar)[XB_TMO])) break; if (_sp > XB_SPIN_CAP) { atomicAdd(&(bar)[XB_TMO], 1u); break; } } } } while (0)
; __device__ __forceinline__ void xcd_barrier(const XcdBarrier& b) {
;     ...
;         unsigned nloc = b.st[0], nx = b.st[1];
;         if (nloc == 0u) { xcd_barrier_complete(bar, b.x, nloc, nx); b.st[0] = nloc; b.st[1] = nx; }
;         const unsigned old = xb_add(&bar[XB_XSUB(b.x)], 1u);
;         const unsigned gen = old / nloc;
;         if (old + 1u == (gen + 1u) * nloc) {
;             __builtin_amdgcn_fence(__ATOMIC_RELEASE, "agent");
;             asm volatile("s_waitcnt vmcnt(0)" ::: "memory");
;             const unsigned og = xb_add(&bar[XB_TOP], 1u);
;             const unsigned tg = og / nx;
;             if (og + 1u == (tg + 1u) * nx) xb_add(&bar[XB_TOPGEN], 1u);
;             else XB_SPIN(xb_ld(&bar[XB_TOPGEN]) == tg, bar);
;             __builtin_amdgcn_fence(__ATOMIC_ACQUIRE, "agent");
;             xb_add(&bar[XB_XGEN(b.x)], 1u);
;             asm volatile("s_waitcnt vmcnt(0)" ::: "memory");
;         } else {
;             XB_SPIN(xb_ld(&bar[XB_XGEN(b.x)]) == gen, bar);
.LBB0_211:
	s_lshl_b32 s6, s65, 8
	v_readlane_b32 s8, v247, 16
	v_readlane_b32 s9, v247, 17
	s_add_u32 s6, s8, s6
	s_addc_u32 s7, s9, 0
	v_mov_b32_e32 v1, 0x1000
	v_mov_b32_e32 v3, 1
	global_atomic_add v3, v1, v3, s[6:7] offset:1024 sc0
	buffer_inv sc1
	v_cvt_f32_u32_e32 v1, v2
	v_sub_u32_e32 v4, 0, v2
	v_rcp_iflag_f32_e32 v1, v1
	s_nop 0
	v_mul_f32_e32 v1, 0x4f7ffffe, v1
	v_cvt_u32_f32_e32 v1, v1
	v_mul_lo_u32 v4, v4, v1
	v_mul_hi_u32 v4, v1, v4
	v_add_u32_e32 v1, v1, v4
	s_waitcnt vmcnt(0)
	v_mul_hi_u32 v1, v3, v1
	v_mul_lo_u32 v4, v1, v2
	v_sub_u32_e32 v4, v3, v4
	v_add_u32_e32 v5, 1, v1
	v_cmp_ge_u32_e32 vcc, v4, v2
	v_add_u32_e32 v3, 1, v3
	s_nop 0
	v_cndmask_b32_e32 v1, v1, v5, vcc
	v_sub_u32_e32 v5, v4, v2
	v_cndmask_b32_e32 v4, v4, v5, vcc
	v_add_u32_e32 v5, 1, v1
	v_cmp_ge_u32_e32 vcc, v4, v2
	s_nop 1
	v_cndmask_b32_e32 v1, v1, v5, vcc
	v_mul_lo_u32 v4, v2, v1
	v_add_u32_e32 v2, v4, v2
	v_cmp_ne_u32_e32 vcc, v3, v2
	s_and_saveexec_b64 s[8:9], vcc
	s_xor_b64 s[8:9], exec, s[8:9]
	s_cbranch_execz .LBB0_225
	s_waitcnt lgkmcnt(0)
	v_mov_b32_e32 v0, 0x2000
	global_load_dword v0, v0, s[6:7] offset:1024 sc1
	s_add_u32 s16, s6, 0x2400
	s_addc_u32 s17, s7, 0
	s_waitcnt vmcnt(0)
	v_cmp_eq_u32_e32 vcc, v0, v1
	s_and_saveexec_b64 s[10:11], vcc
	s_cbranch_execz .LBB0_224
	s_add_u32 s14, s84, 0xc0200
	s_addc_u32 s15, s85, 0
	s_mov_b32 s28, 1
	s_mov_b64 s[18:19], 0
	v_mov_b32_e32 v0, 0
	s_branch .LBB0_215

; __device__ __forceinline__ unsigned xb_ld(unsigned* p)              { return __hip_atomic_load(p, __ATOMIC_RELAXED, __HIP_MEMORY_SCOPE_AGENT); }
; __device__ __forceinline__ unsigned xb_add(unsigned* p, unsigned v) { return __hip_atomic_fetch_add(p, v, __ATOMIC_RELAXED, __HIP_MEMORY_SCOPE_AGENT); }
; #define XB_SPIN(cond, bar) do { unsigned _sp = 0; while (cond) { __builtin_amdgcn_s_sleep(1); \
;     if ((++_sp & 255u) == 0u) { if (xb_ld(&(bar)[XB_TMO])) break; if (_sp > XB_SPIN_CAP) { atomicAdd(&(bar)[XB_TMO], 1u); break; } } } } while (0)
; __device__ __forceinline__ void xcd_barrier(const XcdBarrier& b) {
;     ...
;         unsigned nloc = b.st[0], nx = b.st[1];
;         if (nloc == 0u) { xcd_barrier_complete(bar, b.x, nloc, nx); b.st[0] = nloc; b.st[1] = nx; }
;         const unsigned old = xb_add(&bar[XB_XSUB(b.x)], 1u);
;         const unsigned gen = old / nloc;
;         if (old + 1u == (gen + 1u) * nloc) {
;             __builtin_amdgcn_fence(__ATOMIC_RELEASE, "agent");
;             asm volatile("s_waitcnt vmcnt(0)" ::: "memory");
;             const unsigned og = xb_add(&bar[XB_TOP], 1u);
;             const unsigned tg = og / nx;
;             if (og + 1u == (tg + 1u) * nx) xb_add(&bar[XB_TOPGEN], 1u);
;             else XB_SPIN(xb_ld(&bar[XB_TOPGEN]) == tg, bar);
;             __builtin_amdgcn_fence(__ATOMIC_ACQUIRE, "agent");
;             xb_add(&bar[XB_XGEN(b.x)], 1u);
;             asm volatile("s_waitcnt vmcnt(0)" ::: "memory");
;         } else {
;             XB_SPIN(xb_ld(&bar[XB_XGEN(b.x)]) == gen, bar);
.LBB0_346:
	s_lshl_b32 s6, s65, 8
	s_add_u32 s6, s88, s6
	s_addc_u32 s7, s89, 0
	v_mov_b32_e32 v1, 0x1000
	v_mov_b32_e32 v3, 1
	global_atomic_add v3, v1, v3, s[6:7] offset:1024 sc0
	buffer_inv sc1
	v_cvt_f32_u32_e32 v1, v2
	v_sub_u32_e32 v4, 0, v2
	v_rcp_iflag_f32_e32 v1, v1
	s_nop 0
	v_mul_f32_e32 v1, 0x4f7ffffe, v1
	v_cvt_u32_f32_e32 v1, v1
	v_mul_lo_u32 v4, v4, v1
	v_mul_hi_u32 v4, v1, v4
	v_add_u32_e32 v1, v1, v4
	s_waitcnt vmcnt(0)
	v_mul_hi_u32 v1, v3, v1
	v_mul_lo_u32 v4, v1, v2
	v_sub_u32_e32 v4, v3, v4
	v_add_u32_e32 v5, 1, v1
	v_cmp_ge_u32_e32 vcc, v4, v2
	v_add_u32_e32 v3, 1, v3
	s_nop 0
	v_cndmask_b32_e32 v1, v1, v5, vcc
	v_sub_u32_e32 v5, v4, v2
	v_cndmask_b32_e32 v4, v4, v5, vcc
	v_add_u32_e32 v5, 1, v1
	v_cmp_ge_u32_e32 vcc, v4, v2
	s_nop 1
	v_cndmask_b32_e32 v1, v1, v5, vcc
	v_mul_lo_u32 v4, v2, v1
	v_add_u32_e32 v2, v4, v2
	v_cmp_ne_u32_e32 vcc, v3, v2
	s_and_saveexec_b64 s[8:9], vcc
	s_xor_b64 s[8:9], exec, s[8:9]
	s_cbranch_execz .LBB0_360
	s_waitcnt lgkmcnt(0)
	v_mov_b32_e32 v0, 0x2000
	global_load_dword v0, v0, s[6:7] offset:1024 sc1
	s_add_u32 s20, s6, 0x2400
	s_addc_u32 s21, s7, 0
	s_waitcnt vmcnt(0)
	v_cmp_eq_u32_e32 vcc, v0, v1
	s_and_saveexec_b64 s[10:11], vcc
	s_cbranch_execz .LBB0_359
	s_add_u32 s18, s84, 0xc0200
	s_addc_u32 s19, s85, 0
	s_mov_b32 s34, 1
	s_mov_b64 s[22:23], 0
	v_mov_b32_e32 v0, 0
	s_branch .LBB0_350

; __device__ __forceinline__ unsigned xb_ld(unsigned* p)              { return __hip_atomic_load(p, __ATOMIC_RELAXED, __HIP_MEMORY_SCOPE_AGENT); }
; __device__ __forceinline__ unsigned xb_add(unsigned* p, unsigned v) { return __hip_atomic_fetch_add(p, v, __ATOMIC_RELAXED, __HIP_MEMORY_SCOPE_AGENT); }
; #define XB_SPIN(cond, bar) do { unsigned _sp = 0; while (cond) { __builtin_amdgcn_s_sleep(1); \
;     if ((++_sp & 255u) == 0u) { if (xb_ld(&(bar)[XB_TMO])) break; if (_sp > XB_SPIN_CAP) { atomicAdd(&(bar)[XB_TMO], 1u); break; } } } } while (0)
; __device__ __forceinline__ void xcd_barrier(const XcdBarrier& b) {
;     ...
;         unsigned nloc = b.st[0], nx = b.st[1];
;         if (nloc == 0u) { xcd_barrier_complete(bar, b.x, nloc, nx); b.st[0] = nloc; b.st[1] = nx; }
;         const unsigned old = xb_add(&bar[XB_XSUB(b.x)], 1u);
;         const unsigned gen = old / nloc;
;         if (old + 1u == (gen + 1u) * nloc) {
;             __builtin_amdgcn_fence(__ATOMIC_RELEASE, "agent");
;             asm volatile("s_waitcnt vmcnt(0)" ::: "memory");
;             const unsigned og = xb_add(&bar[XB_TOP], 1u);
;             const unsigned tg = og / nx;
;             if (og + 1u == (tg + 1u) * nx) xb_add(&bar[XB_TOPGEN], 1u);
;             else XB_SPIN(xb_ld(&bar[XB_TOPGEN]) == tg, bar);
;             __builtin_amdgcn_fence(__ATOMIC_ACQUIRE, "agent");
;             xb_add(&bar[XB_XGEN(b.x)], 1u);
;             asm volatile("s_waitcnt vmcnt(0)" ::: "memory");
;         } else {
;             XB_SPIN(xb_ld(&bar[XB_XGEN(b.x)]) == gen, bar);
.LBB0_529:
	s_lshl_b32 s8, s65, 8
	s_add_u32 s8, s88, s8
	s_addc_u32 s9, s89, 0
	v_mov_b32_e32 v1, 0x1000
	v_mov_b32_e32 v3, 1
	global_atomic_add v3, v1, v3, s[8:9] offset:1024 sc0
	buffer_inv sc1
	v_cvt_f32_u32_e32 v1, v2
	v_sub_u32_e32 v4, 0, v2
	v_rcp_iflag_f32_e32 v1, v1
	s_nop 0
	v_mul_f32_e32 v1, 0x4f7ffffe, v1
	v_cvt_u32_f32_e32 v1, v1
	v_mul_lo_u32 v4, v4, v1
	v_mul_hi_u32 v4, v1, v4
	v_add_u32_e32 v1, v1, v4
	s_waitcnt vmcnt(0)
	v_mul_hi_u32 v1, v3, v1
	v_mul_lo_u32 v4, v1, v2
	v_sub_u32_e32 v4, v3, v4
	v_add_u32_e32 v5, 1, v1
	v_cmp_ge_u32_e32 vcc, v4, v2
	v_add_u32_e32 v3, 1, v3
	s_nop 0
	v_cndmask_b32_e32 v1, v1, v5, vcc
	v_sub_u32_e32 v5, v4, v2
	v_cndmask_b32_e32 v4, v4, v5, vcc
	v_add_u32_e32 v5, 1, v1
	v_cmp_ge_u32_e32 vcc, v4, v2
	s_nop 1
	v_cndmask_b32_e32 v1, v1, v5, vcc
	v_mul_lo_u32 v4, v2, v1
	v_add_u32_e32 v2, v4, v2
	v_cmp_ne_u32_e32 vcc, v3, v2
	s_and_saveexec_b64 s[10:11], vcc
	s_xor_b64 s[10:11], exec, s[10:11]
	s_cbranch_execz .LBB0_543
	s_waitcnt lgkmcnt(0)
	v_mov_b32_e32 v0, 0x2000
	global_load_dword v0, v0, s[8:9] offset:1024 sc1
	s_add_u32 s22, s8, 0x2400
	s_addc_u32 s23, s9, 0
	s_waitcnt vmcnt(0)
	v_cmp_eq_u32_e32 vcc, v0, v1
	s_and_saveexec_b64 s[18:19], vcc
	s_cbranch_execz .LBB0_542
	s_add_u32 s20, s84, 0xc0200
	s_addc_u32 s21, s85, 0
	s_mov_b32 s36, 1
	s_mov_b64 s[24:25], 0
	v_mov_b32_e32 v0, 0
	s_branch .LBB0_533

; __device__ __forceinline__ unsigned xb_ld(unsigned* p)              { return __hip_atomic_load(p, __ATOMIC_RELAXED, __HIP_MEMORY_SCOPE_AGENT); }
; #define XB_SPIN(cond, bar) do { unsigned _sp = 0; while (cond) { __builtin_amdgcn_s_sleep(1); \
;     if ((++_sp & 255u) == 0u) { if (xb_ld(&(bar)[XB_TMO])) break; if (_sp > XB_SPIN_CAP) { atomicAdd(&(bar)[XB_TMO], 1u); break; } } } } while (0)
; __device__ __forceinline__ void xcd_barrier(const XcdBarrier& b) {
;     ...
;             XB_SPIN(xb_ld(&bar[XB_XGEN(b.x)]) == gen, bar);
;             __builtin_amdgcn_fence(__ATOMIC_ACQUIRE, "agent");
;             asm volatile("s_waitcnt vmcnt(0)" ::: "memory");
.LBB0_542:
	s_or_b64 exec, exec, s[18:19]
	s_waitcnt vmcnt(0)
	s_waitcnt vmcnt(0)

; __device__ __forceinline__ unsigned xb_ld(unsigned* p)              { return __hip_atomic_load(p, __ATOMIC_RELAXED, __HIP_MEMORY_SCOPE_AGENT); }
; __device__ __forceinline__ unsigned xb_add(unsigned* p, unsigned v) { return __hip_atomic_fetch_add(p, v, __ATOMIC_RELAXED, __HIP_MEMORY_SCOPE_AGENT); }
; #define XB_SPIN(cond, bar) do { unsigned _sp = 0; while (cond) { __builtin_amdgcn_s_sleep(1); \
;     if ((++_sp & 255u) == 0u) { if (xb_ld(&(bar)[XB_TMO])) break; if (_sp > XB_SPIN_CAP) { atomicAdd(&(bar)[XB_TMO], 1u); break; } } } } while (0)
; __device__ __forceinline__ void xcd_barrier(const XcdBarrier& b) {
;     ...
;             else XB_SPIN(xb_ld(&bar[XB_TOPGEN]) == tg, bar);
;             __builtin_amdgcn_fence(__ATOMIC_ACQUIRE, "agent");
;             xb_add(&bar[XB_XGEN(b.x)], 1u);
.LBB0_560:
	s_or_b64 exec, exec, s[10:11]
	v_mov_b32_e32 v0, 0x2000
	v_mov_b32_e32 v1, 1
	s_waitcnt vmcnt(0)
	global_atomic_add v0, v1, s[8:9] offset:1024
	s_waitcnt vmcnt(0)

; __device__ __forceinline__ unsigned xb_ld(unsigned* p)              { return __hip_atomic_load(p, __ATOMIC_RELAXED, __HIP_MEMORY_SCOPE_AGENT); }
; __device__ __forceinline__ unsigned xb_add(unsigned* p, unsigned v) { return __hip_atomic_fetch_add(p, v, __ATOMIC_RELAXED, __HIP_MEMORY_SCOPE_AGENT); }
; #define XB_SPIN(cond, bar) do { unsigned _sp = 0; while (cond) { __builtin_amdgcn_s_sleep(1); \
;     if ((++_sp & 255u) == 0u) { if (xb_ld(&(bar)[XB_TMO])) break; if (_sp > XB_SPIN_CAP) { atomicAdd(&(bar)[XB_TMO], 1u); break; } } } } while (0)
; __device__ __forceinline__ void xcd_barrier(const XcdBarrier& b) {
;     ...
;         unsigned nloc = b.st[0], nx = b.st[1];
;         if (nloc == 0u) { xcd_barrier_complete(bar, b.x, nloc, nx); b.st[0] = nloc; b.st[1] = nx; }
;         const unsigned old = xb_add(&bar[XB_XSUB(b.x)], 1u);
;         const unsigned gen = old / nloc;
;         if (old + 1u == (gen + 1u) * nloc) {
;             __builtin_amdgcn_fence(__ATOMIC_RELEASE, "agent");
;             asm volatile("s_waitcnt vmcnt(0)" ::: "memory");
;             const unsigned og = xb_add(&bar[XB_TOP], 1u);
;             const unsigned tg = og / nx;
;             if (og + 1u == (tg + 1u) * nx) xb_add(&bar[XB_TOPGEN], 1u);
;             else XB_SPIN(xb_ld(&bar[XB_TOPGEN]) == tg, bar);
;             __builtin_amdgcn_fence(__ATOMIC_ACQUIRE, "agent");
;             xb_add(&bar[XB_XGEN(b.x)], 1u);
;             asm volatile("s_waitcnt vmcnt(0)" ::: "memory");
;         } else {
;             XB_SPIN(xb_ld(&bar[XB_XGEN(b.x)]) == gen, bar);
.LBB0_598:
	s_lshl_b32 s6, s65, 8
	s_add_u32 s6, s88, s6
	s_addc_u32 s7, s89, 0
	v_mov_b32_e32 v1, 0x1000
	v_mov_b32_e32 v3, 1
	global_atomic_add v3, v1, v3, s[6:7] offset:1024 sc0
	buffer_inv sc1
	v_cvt_f32_u32_e32 v1, v2
	v_sub_u32_e32 v4, 0, v2
	v_rcp_iflag_f32_e32 v1, v1
	s_nop 0
	v_mul_f32_e32 v1, 0x4f7ffffe, v1
	v_cvt_u32_f32_e32 v1, v1
	v_mul_lo_u32 v4, v4, v1
	v_mul_hi_u32 v4, v1, v4
	v_add_u32_e32 v1, v1, v4
	s_waitcnt vmcnt(0)
	v_mul_hi_u32 v1, v3, v1
	v_mul_lo_u32 v4, v1, v2
	v_sub_u32_e32 v4, v3, v4
	v_add_u32_e32 v5, 1, v1
	v_cmp_ge_u32_e32 vcc, v4, v2
	v_add_u32_e32 v3, 1, v3
	s_nop 0
	v_cndmask_b32_e32 v1, v1, v5, vcc
	v_sub_u32_e32 v5, v4, v2
	v_cndmask_b32_e32 v4, v4, v5, vcc
	v_add_u32_e32 v5, 1, v1
	v_cmp_ge_u32_e32 vcc, v4, v2
	s_nop 1
	v_cndmask_b32_e32 v1, v1, v5, vcc
	v_mul_lo_u32 v4, v2, v1
	v_add_u32_e32 v2, v4, v2
	v_cmp_ne_u32_e32 vcc, v3, v2
	s_and_saveexec_b64 s[8:9], vcc
	s_xor_b64 s[8:9], exec, s[8:9]
	s_cbranch_execz .LBB0_612
	s_waitcnt lgkmcnt(0)
	v_mov_b32_e32 v0, 0x2000
	global_load_dword v0, v0, s[6:7] offset:1024 sc1
	s_add_u32 s22, s6, 0x2400
	s_addc_u32 s23, s7, 0
	s_waitcnt vmcnt(0)
	v_cmp_eq_u32_e32 vcc, v0, v1
	s_and_saveexec_b64 s[10:11], vcc
	s_cbranch_execz .LBB0_611
	s_add_u32 s20, s84, 0xc0200
	s_addc_u32 s21, s85, 0
	s_mov_b32 s36, 1
	s_mov_b64 s[24:25], 0
	v_mov_b32_e32 v0, 0
	s_branch .LBB0_602

; __device__ __forceinline__ unsigned xb_ld(unsigned* p)              { return __hip_atomic_load(p, __ATOMIC_RELAXED, __HIP_MEMORY_SCOPE_AGENT); }
; __device__ __forceinline__ unsigned xb_add(unsigned* p, unsigned v) { return __hip_atomic_fetch_add(p, v, __ATOMIC_RELAXED, __HIP_MEMORY_SCOPE_AGENT); }
; #define XB_SPIN(cond, bar) do { unsigned _sp = 0; while (cond) { __builtin_amdgcn_s_sleep(1); \
;     if ((++_sp & 255u) == 0u) { if (xb_ld(&(bar)[XB_TMO])) break; if (_sp > XB_SPIN_CAP) { atomicAdd(&(bar)[XB_TMO], 1u); break; } } } } while (0)
; __device__ __forceinline__ void xcd_barrier(const XcdBarrier& b) {
;     ...
;         unsigned nloc = b.st[0], nx = b.st[1];
;         if (nloc == 0u) { xcd_barrier_complete(bar, b.x, nloc, nx); b.st[0] = nloc; b.st[1] = nx; }
;         const unsigned old = xb_add(&bar[XB_XSUB(b.x)], 1u);
;         const unsigned gen = old / nloc;
;         if (old + 1u == (gen + 1u) * nloc) {
;             __builtin_amdgcn_fence(__ATOMIC_RELEASE, "agent");
;             asm volatile("s_waitcnt vmcnt(0)" ::: "memory");
;             const unsigned og = xb_add(&bar[XB_TOP], 1u);
;             const unsigned tg = og / nx;
;             if (og + 1u == (tg + 1u) * nx) xb_add(&bar[XB_TOPGEN], 1u);
;             else XB_SPIN(xb_ld(&bar[XB_TOPGEN]) == tg, bar);
;             __builtin_amdgcn_fence(__ATOMIC_ACQUIRE, "agent");
;             xb_add(&bar[XB_XGEN(b.x)], 1u);
;             asm volatile("s_waitcnt vmcnt(0)" ::: "memory");
;         } else {
;             XB_SPIN(xb_ld(&bar[XB_XGEN(b.x)]) == gen, bar);
.LBB0_683:
	s_lshl_b32 s3, s65, 8
	s_add_u32 s6, s88, s3
	s_addc_u32 s7, s89, 0
	v_mov_b32_e32 v1, 0x1000
	v_mov_b32_e32 v3, 1
	global_atomic_add v3, v1, v3, s[6:7] offset:1024 sc0
	buffer_inv sc1
	v_cvt_f32_u32_e32 v1, v2
	v_sub_u32_e32 v4, 0, v2
	v_rcp_iflag_f32_e32 v1, v1
	s_nop 0
	v_mul_f32_e32 v1, 0x4f7ffffe, v1
	v_cvt_u32_f32_e32 v1, v1
	v_mul_lo_u32 v4, v4, v1
	v_mul_hi_u32 v4, v1, v4
	v_add_u32_e32 v1, v1, v4
	s_waitcnt vmcnt(0)
	v_mul_hi_u32 v1, v3, v1
	v_mul_lo_u32 v4, v1, v2
	v_sub_u32_e32 v4, v3, v4
	v_add_u32_e32 v5, 1, v1
	v_cmp_ge_u32_e32 vcc, v4, v2
	v_add_u32_e32 v3, 1, v3
	s_nop 0
	v_cndmask_b32_e32 v1, v1, v5, vcc
	v_sub_u32_e32 v5, v4, v2
	v_cndmask_b32_e32 v4, v4, v5, vcc
	v_add_u32_e32 v5, 1, v1
	v_cmp_ge_u32_e32 vcc, v4, v2
	s_nop 1
	v_cndmask_b32_e32 v1, v1, v5, vcc
	v_mul_lo_u32 v4, v2, v1
	v_add_u32_e32 v2, v4, v2
	v_cmp_ne_u32_e32 vcc, v3, v2
	s_and_saveexec_b64 s[8:9], vcc
	s_xor_b64 s[8:9], exec, s[8:9]
	s_cbranch_execz .LBB0_697
	s_waitcnt lgkmcnt(0)
	v_mov_b32_e32 v0, 0x2000
	global_load_dword v0, v0, s[6:7] offset:1024 sc1
	s_add_u32 s24, s6, 0x2400
	s_addc_u32 s25, s7, 0
	s_waitcnt vmcnt(0)
	v_cmp_eq_u32_e32 vcc, v0, v1
	s_and_saveexec_b64 s[10:11], vcc
	s_cbranch_execz .LBB0_696
	s_add_u32 s22, s84, 0xc0200
	s_addc_u32 s23, s85, 0
	s_mov_b32 s3, 1
	s_mov_b64 s[26:27], 0
	v_mov_b32_e32 v0, 0
	s_branch .LBB0_687

; __device__ __forceinline__ unsigned xb_ld(unsigned* p)              { return __hip_atomic_load(p, __ATOMIC_RELAXED, __HIP_MEMORY_SCOPE_AGENT); }
; __device__ __forceinline__ unsigned xb_add(unsigned* p, unsigned v) { return __hip_atomic_fetch_add(p, v, __ATOMIC_RELAXED, __HIP_MEMORY_SCOPE_AGENT); }
; #define XB_SPIN(cond, bar) do { unsigned _sp = 0; while (cond) { __builtin_amdgcn_s_sleep(1); \
;     if ((++_sp & 255u) == 0u) { if (xb_ld(&(bar)[XB_TMO])) break; if (_sp > XB_SPIN_CAP) { atomicAdd(&(bar)[XB_TMO], 1u); break; } } } } while (0)
; __device__ __forceinline__ void xcd_barrier(const XcdBarrier& b) {
;     ...
;         unsigned nloc = b.st[0], nx = b.st[1];
;         if (nloc == 0u) { xcd_barrier_complete(bar, b.x, nloc, nx); b.st[0] = nloc; b.st[1] = nx; }
;         const unsigned old = xb_add(&bar[XB_XSUB(b.x)], 1u);
;         const unsigned gen = old / nloc;
;         if (old + 1u == (gen + 1u) * nloc) {
;             __builtin_amdgcn_fence(__ATOMIC_RELEASE, "agent");
;             asm volatile("s_waitcnt vmcnt(0)" ::: "memory");
;             const unsigned og = xb_add(&bar[XB_TOP], 1u);
;             const unsigned tg = og / nx;
;             if (og + 1u == (tg + 1u) * nx) xb_add(&bar[XB_TOPGEN], 1u);
;             else XB_SPIN(xb_ld(&bar[XB_TOPGEN]) == tg, bar);
;             __builtin_amdgcn_fence(__ATOMIC_ACQUIRE, "agent");
;             xb_add(&bar[XB_XGEN(b.x)], 1u);
;             asm volatile("s_waitcnt vmcnt(0)" ::: "memory");
;         } else {
;             XB_SPIN(xb_ld(&bar[XB_XGEN(b.x)]) == gen, bar);
.LBB0_907:
	s_lshl_b32 s6, s65, 8
	s_add_u32 s6, s88, s6
	s_addc_u32 s7, s89, 0
	v_mov_b32_e32 v1, 0x1000
	v_mov_b32_e32 v3, 1
	global_atomic_add v3, v1, v3, s[6:7] offset:1024 sc0
	buffer_inv sc1
	v_cvt_f32_u32_e32 v1, v2
	v_sub_u32_e32 v4, 0, v2
	v_rcp_iflag_f32_e32 v1, v1
	s_nop 0
	v_mul_f32_e32 v1, 0x4f7ffffe, v1
	v_cvt_u32_f32_e32 v1, v1
	v_mul_lo_u32 v4, v4, v1
	v_mul_hi_u32 v4, v1, v4
	v_add_u32_e32 v1, v1, v4
	s_waitcnt vmcnt(0)
	v_mul_hi_u32 v1, v3, v1
	v_mul_lo_u32 v4, v1, v2
	v_sub_u32_e32 v4, v3, v4
	v_add_u32_e32 v5, 1, v1
	v_cmp_ge_u32_e32 vcc, v4, v2
	v_add_u32_e32 v3, 1, v3
	s_nop 0
	v_cndmask_b32_e32 v1, v1, v5, vcc
	v_sub_u32_e32 v5, v4, v2
	v_cndmask_b32_e32 v4, v4, v5, vcc
	v_add_u32_e32 v5, 1, v1
	v_cmp_ge_u32_e32 vcc, v4, v2
	s_nop 1
	v_cndmask_b32_e32 v1, v1, v5, vcc
	v_mul_lo_u32 v4, v2, v1
	v_add_u32_e32 v2, v4, v2
	v_cmp_ne_u32_e32 vcc, v3, v2
	s_and_saveexec_b64 s[8:9], vcc
	s_xor_b64 s[8:9], exec, s[8:9]
	s_cbranch_execz .LBB0_921
	s_waitcnt lgkmcnt(0)
	v_mov_b32_e32 v0, 0x2000
	global_load_dword v0, v0, s[6:7] offset:1024 sc1
	s_add_u32 s26, s6, 0x2400
	s_addc_u32 s27, s7, 0
	s_waitcnt vmcnt(0)
	v_cmp_eq_u32_e32 vcc, v0, v1
	s_and_saveexec_b64 s[10:11], vcc
	s_cbranch_execz .LBB0_920
	s_add_u32 s24, s84, 0xc0200
	s_addc_u32 s25, s85, 0
	s_mov_b32 s40, 1
	s_mov_b64 s[28:29], 0
	v_mov_b32_e32 v0, 0
	s_branch .LBB0_911

; __device__ __forceinline__ unsigned xb_ld(unsigned* p)              { return __hip_atomic_load(p, __ATOMIC_RELAXED, __HIP_MEMORY_SCOPE_AGENT); }
; __device__ __forceinline__ unsigned xb_add(unsigned* p, unsigned v) { return __hip_atomic_fetch_add(p, v, __ATOMIC_RELAXED, __HIP_MEMORY_SCOPE_AGENT); }
; #define XB_SPIN(cond, bar) do { unsigned _sp = 0; while (cond) { __builtin_amdgcn_s_sleep(1); \
;     if ((++_sp & 255u) == 0u) { if (xb_ld(&(bar)[XB_TMO])) break; if (_sp > XB_SPIN_CAP) { atomicAdd(&(bar)[XB_TMO], 1u); break; } } } } while (0)
; __device__ __forceinline__ void xcd_barrier(const XcdBarrier& b) {
;     ...
;         unsigned nloc = b.st[0], nx = b.st[1];
;         if (nloc == 0u) { xcd_barrier_complete(bar, b.x, nloc, nx); b.st[0] = nloc; b.st[1] = nx; }
;         const unsigned old = xb_add(&bar[XB_XSUB(b.x)], 1u);
;         const unsigned gen = old / nloc;
;         if (old + 1u == (gen + 1u) * nloc) {
;             __builtin_amdgcn_fence(__ATOMIC_RELEASE, "agent");
;             asm volatile("s_waitcnt vmcnt(0)" ::: "memory");
;             const unsigned og = xb_add(&bar[XB_TOP], 1u);
;             const unsigned tg = og / nx;
;             if (og + 1u == (tg + 1u) * nx) xb_add(&bar[XB_TOPGEN], 1u);
;             else XB_SPIN(xb_ld(&bar[XB_TOPGEN]) == tg, bar);
;             __builtin_amdgcn_fence(__ATOMIC_ACQUIRE, "agent");
;             xb_add(&bar[XB_XGEN(b.x)], 1u);
;             asm volatile("s_waitcnt vmcnt(0)" ::: "memory");
;         } else {
;             XB_SPIN(xb_ld(&bar[XB_XGEN(b.x)]) == gen, bar);
.LBB0_1024:
	s_lshl_b32 s6, s65, 8
	s_add_u32 s6, s88, s6
	s_addc_u32 s7, s89, 0
	v_mov_b32_e32 v1, 0x1000
	v_mov_b32_e32 v3, 1
	global_atomic_add v3, v1, v3, s[6:7] offset:1024 sc0
	buffer_inv sc1
	v_cvt_f32_u32_e32 v1, v2
	v_sub_u32_e32 v4, 0, v2
	v_rcp_iflag_f32_e32 v1, v1
	s_nop 0
	v_mul_f32_e32 v1, 0x4f7ffffe, v1
	v_cvt_u32_f32_e32 v1, v1
	v_mul_lo_u32 v4, v4, v1
	v_mul_hi_u32 v4, v1, v4
	v_add_u32_e32 v1, v1, v4
	s_waitcnt vmcnt(0)
	v_mul_hi_u32 v1, v3, v1
	v_mul_lo_u32 v4, v1, v2
	v_sub_u32_e32 v4, v3, v4
	v_add_u32_e32 v5, 1, v1
	v_cmp_ge_u32_e32 vcc, v4, v2
	v_add_u32_e32 v3, 1, v3
	s_nop 0
	v_cndmask_b32_e32 v1, v1, v5, vcc
	v_sub_u32_e32 v5, v4, v2
	v_cndmask_b32_e32 v4, v4, v5, vcc
	v_add_u32_e32 v5, 1, v1
	v_cmp_ge_u32_e32 vcc, v4, v2
	s_nop 1
	v_cndmask_b32_e32 v1, v1, v5, vcc
	v_mul_lo_u32 v4, v2, v1
	v_add_u32_e32 v2, v4, v2
	v_cmp_ne_u32_e32 vcc, v3, v2
	s_and_saveexec_b64 s[8:9], vcc
	s_xor_b64 s[8:9], exec, s[8:9]
	s_cbranch_execz .LBB0_1038
	s_waitcnt lgkmcnt(0)
	v_mov_b32_e32 v0, 0x2000
	global_load_dword v0, v0, s[6:7] offset:1024 sc1
	s_add_u32 s24, s6, 0x2400
	s_addc_u32 s25, s7, 0
	s_waitcnt vmcnt(0)
	v_cmp_eq_u32_e32 vcc, v0, v1
	s_and_saveexec_b64 s[10:11], vcc
	s_cbranch_execz .LBB0_1037
	s_add_u32 s22, s84, 0xc0200
	s_addc_u32 s23, s85, 0
	s_mov_b32 s38, 1
	s_mov_b64 s[26:27], 0
	v_mov_b32_e32 v0, 0
	s_branch .LBB0_1028

; __device__ __forceinline__ unsigned xb_ld(unsigned* p)              { return __hip_atomic_load(p, __ATOMIC_RELAXED, __HIP_MEMORY_SCOPE_AGENT); }
; __device__ __forceinline__ unsigned xb_add(unsigned* p, unsigned v) { return __hip_atomic_fetch_add(p, v, __ATOMIC_RELAXED, __HIP_MEMORY_SCOPE_AGENT); }
; #define XB_SPIN(cond, bar) do { unsigned _sp = 0; while (cond) { __builtin_amdgcn_s_sleep(1); \
;     if ((++_sp & 255u) == 0u) { if (xb_ld(&(bar)[XB_TMO])) break; if (_sp > XB_SPIN_CAP) { atomicAdd(&(bar)[XB_TMO], 1u); break; } } } } while (0)
; __device__ __forceinline__ void xcd_barrier(const XcdBarrier& b) {
;     ...
;         unsigned nloc = b.st[0], nx = b.st[1];
;         if (nloc == 0u) { xcd_barrier_complete(bar, b.x, nloc, nx); b.st[0] = nloc; b.st[1] = nx; }
;         const unsigned old = xb_add(&bar[XB_XSUB(b.x)], 1u);
;         const unsigned gen = old / nloc;
;         if (old + 1u == (gen + 1u) * nloc) {
;             __builtin_amdgcn_fence(__ATOMIC_RELEASE, "agent");
;             asm volatile("s_waitcnt vmcnt(0)" ::: "memory");
;             const unsigned og = xb_add(&bar[XB_TOP], 1u);
;             const unsigned tg = og / nx;
;             if (og + 1u == (tg + 1u) * nx) xb_add(&bar[XB_TOPGEN], 1u);
;             else XB_SPIN(xb_ld(&bar[XB_TOPGEN]) == tg, bar);
;             __builtin_amdgcn_fence(__ATOMIC_ACQUIRE, "agent");
;             xb_add(&bar[XB_XGEN(b.x)], 1u);
;             asm volatile("s_waitcnt vmcnt(0)" ::: "memory");
;         } else {
;             XB_SPIN(xb_ld(&bar[XB_XGEN(b.x)]) == gen, bar);
.LBB0_1180:
	s_lshl_b32 s3, s65, 8
	s_add_u32 s6, s88, s3
	s_addc_u32 s7, s89, 0
	v_mov_b32_e32 v1, 0x1000
	v_mov_b32_e32 v3, 1
	global_atomic_add v3, v1, v3, s[6:7] offset:1024 sc0
	buffer_inv sc1
	v_cvt_f32_u32_e32 v1, v2
	v_sub_u32_e32 v4, 0, v2
	v_rcp_iflag_f32_e32 v1, v1
	s_nop 0
	v_mul_f32_e32 v1, 0x4f7ffffe, v1
	v_cvt_u32_f32_e32 v1, v1
	v_mul_lo_u32 v4, v4, v1
	v_mul_hi_u32 v4, v1, v4
	v_add_u32_e32 v1, v1, v4
	s_waitcnt vmcnt(0)
	v_mul_hi_u32 v1, v3, v1
	v_mul_lo_u32 v4, v1, v2
	v_sub_u32_e32 v4, v3, v4
	v_add_u32_e32 v5, 1, v1
	v_cmp_ge_u32_e32 vcc, v4, v2
	v_add_u32_e32 v3, 1, v3
	s_nop 0
	v_cndmask_b32_e32 v1, v1, v5, vcc
	v_sub_u32_e32 v5, v4, v2
	v_cndmask_b32_e32 v4, v4, v5, vcc
	v_add_u32_e32 v5, 1, v1
	v_cmp_ge_u32_e32 vcc, v4, v2
	s_nop 1
	v_cndmask_b32_e32 v1, v1, v5, vcc
	v_mul_lo_u32 v4, v2, v1
	v_add_u32_e32 v2, v4, v2
	v_cmp_ne_u32_e32 vcc, v3, v2
	s_and_saveexec_b64 s[8:9], vcc
	s_xor_b64 s[8:9], exec, s[8:9]
	s_cbranch_execz .LBB0_1194
	s_waitcnt lgkmcnt(0)
	v_mov_b32_e32 v0, 0x2000
	global_load_dword v0, v0, s[6:7] offset:1024 sc1
	s_add_u32 s14, s6, 0x2400
	s_addc_u32 s15, s7, 0
	s_waitcnt vmcnt(0)
	v_cmp_eq_u32_e32 vcc, v0, v1
	s_and_saveexec_b64 s[10:11], vcc
	s_cbranch_execz .LBB0_1193
	s_add_u32 s12, s84, 0xc0200
	s_addc_u32 s13, s85, 0
	s_mov_b32 s3, 1
	s_mov_b64 s[16:17], 0
	v_mov_b32_e32 v0, 0
	s_branch .LBB0_1184

; __device__ __forceinline__ unsigned xb_ld(unsigned* p)              { return __hip_atomic_load(p, __ATOMIC_RELAXED, __HIP_MEMORY_SCOPE_AGENT); }
; __device__ __forceinline__ unsigned xb_add(unsigned* p, unsigned v) { return __hip_atomic_fetch_add(p, v, __ATOMIC_RELAXED, __HIP_MEMORY_SCOPE_AGENT); }
; #define XB_SPIN(cond, bar) do { unsigned _sp = 0; while (cond) { __builtin_amdgcn_s_sleep(1); \
;     if ((++_sp & 255u) == 0u) { if (xb_ld(&(bar)[XB_TMO])) break; if (_sp > XB_SPIN_CAP) { atomicAdd(&(bar)[XB_TMO], 1u); break; } } } } while (0)
; __device__ __forceinline__ void xcd_barrier(const XcdBarrier& b) {
;     ...
;         unsigned nloc = b.st[0], nx = b.st[1];
;         if (nloc == 0u) { xcd_barrier_complete(bar, b.x, nloc, nx); b.st[0] = nloc; b.st[1] = nx; }
;         const unsigned old = xb_add(&bar[XB_XSUB(b.x)], 1u);
;         const unsigned gen = old / nloc;
;         if (old + 1u == (gen + 1u) * nloc) {
;             __builtin_amdgcn_fence(__ATOMIC_RELEASE, "agent");
;             asm volatile("s_waitcnt vmcnt(0)" ::: "memory");
;             const unsigned og = xb_add(&bar[XB_TOP], 1u);
;             const unsigned tg = og / nx;
;             if (og + 1u == (tg + 1u) * nx) xb_add(&bar[XB_TOPGEN], 1u);
;             else XB_SPIN(xb_ld(&bar[XB_TOPGEN]) == tg, bar);
;             __builtin_amdgcn_fence(__ATOMIC_ACQUIRE, "agent");
;             xb_add(&bar[XB_XGEN(b.x)], 1u);
;             asm volatile("s_waitcnt vmcnt(0)" ::: "memory");
;         } else {
;             XB_SPIN(xb_ld(&bar[XB_XGEN(b.x)]) == gen, bar);
.LBB0_1255:
	s_lshl_b32 s4, s65, 8
	s_add_u32 s4, s88, s4
	s_addc_u32 s5, s89, 0
	v_mov_b32_e32 v1, 0x1000
	v_mov_b32_e32 v3, 1
	global_atomic_add v3, v1, v3, s[4:5] offset:1024 sc0
	buffer_inv sc1
	v_cvt_f32_u32_e32 v1, v2
	v_sub_u32_e32 v4, 0, v2
	v_rcp_iflag_f32_e32 v1, v1
	s_nop 0
	v_mul_f32_e32 v1, 0x4f7ffffe, v1
	v_cvt_u32_f32_e32 v1, v1
	v_mul_lo_u32 v4, v4, v1
	v_mul_hi_u32 v4, v1, v4
	v_add_u32_e32 v1, v1, v4
	s_waitcnt vmcnt(0)
	v_mul_hi_u32 v1, v3, v1
	v_mul_lo_u32 v4, v1, v2
	v_sub_u32_e32 v4, v3, v4
	v_add_u32_e32 v5, 1, v1
	v_cmp_ge_u32_e32 vcc, v4, v2
	v_add_u32_e32 v3, 1, v3
	s_nop 0
	v_cndmask_b32_e32 v1, v1, v5, vcc
	v_sub_u32_e32 v5, v4, v2
	v_cndmask_b32_e32 v4, v4, v5, vcc
	v_add_u32_e32 v5, 1, v1
	v_cmp_ge_u32_e32 vcc, v4, v2
	s_nop 1
	v_cndmask_b32_e32 v1, v1, v5, vcc
	v_mul_lo_u32 v4, v2, v1
	v_add_u32_e32 v2, v4, v2
	v_cmp_ne_u32_e32 vcc, v3, v2
	s_and_saveexec_b64 s[6:7], vcc
	s_xor_b64 s[6:7], exec, s[6:7]
	s_cbranch_execz .LBB0_1269
	s_waitcnt lgkmcnt(0)
	v_mov_b32_e32 v0, 0x2000
	global_load_dword v0, v0, s[4:5] offset:1024 sc1
	s_add_u32 s12, s4, 0x2400
	s_addc_u32 s13, s5, 0
	s_waitcnt vmcnt(0)
	v_cmp_eq_u32_e32 vcc, v0, v1
	s_and_saveexec_b64 s[8:9], vcc
	s_cbranch_execz .LBB0_1268
	s_add_u32 s10, s84, 0xc0200
	s_addc_u32 s11, s85, 0
	s_mov_b32 s24, 1
	s_mov_b64 s[14:15], 0
	v_mov_b32_e32 v0, 0
	s_branch .LBB0_1259

; __device__ __forceinline__ unsigned xb_ld(unsigned* p)              { return __hip_atomic_load(p, __ATOMIC_RELAXED, __HIP_MEMORY_SCOPE_AGENT); }
; #define XB_SPIN(cond, bar) do { unsigned _sp = 0; while (cond) { __builtin_amdgcn_s_sleep(1); \
;     if ((++_sp & 255u) == 0u) { if (xb_ld(&(bar)[XB_TMO])) break; if (_sp > XB_SPIN_CAP) { atomicAdd(&(bar)[XB_TMO], 1u); break; } } } } while (0)
; __device__ __forceinline__ void xcd_barrier(const XcdBarrier& b) {
;     ...
;             XB_SPIN(xb_ld(&bar[XB_XGEN(b.x)]) == gen, bar);
;             __builtin_amdgcn_fence(__ATOMIC_ACQUIRE, "agent");
;             asm volatile("s_waitcnt vmcnt(0)" ::: "memory");
.LBB0_1268:
	s_or_b64 exec, exec, s[8:9]
	s_waitcnt vmcnt(0)
	s_waitcnt vmcnt(0)

; __device__ __forceinline__ unsigned xb_ld(unsigned* p)              { return __hip_atomic_load(p, __ATOMIC_RELAXED, __HIP_MEMORY_SCOPE_AGENT); }
; __device__ __forceinline__ unsigned xb_add(unsigned* p, unsigned v) { return __hip_atomic_fetch_add(p, v, __ATOMIC_RELAXED, __HIP_MEMORY_SCOPE_AGENT); }
; #define XB_SPIN(cond, bar) do { unsigned _sp = 0; while (cond) { __builtin_amdgcn_s_sleep(1); \
;     if ((++_sp & 255u) == 0u) { if (xb_ld(&(bar)[XB_TMO])) break; if (_sp > XB_SPIN_CAP) { atomicAdd(&(bar)[XB_TMO], 1u); break; } } } } while (0)
; __device__ __forceinline__ void xcd_barrier(const XcdBarrier& b) {
;     ...
;             else XB_SPIN(xb_ld(&bar[XB_TOPGEN]) == tg, bar);
;             __builtin_amdgcn_fence(__ATOMIC_ACQUIRE, "agent");
;             xb_add(&bar[XB_XGEN(b.x)], 1u);
.LBB0_1286:
	s_or_b64 exec, exec, s[6:7]
	v_mov_b32_e32 v0, 0x2000
	v_mov_b32_e32 v1, 1
	s_waitcnt vmcnt(0)
	global_atomic_add v0, v1, s[4:5] offset:1024
	s_waitcnt vmcnt(0)
